# counted waits: drop the compiler's full vmcnt drain after the counted LDS-DMA waits at the start of the five row-scaled GEMM phases
# speedup vs baseline: 1.0083x; 1.0083x over previous
; #define PG8_STAGE(bufoff, gbase, voff) do { _Pragma("unroll") for (int _i = 0; _i < 2; ++_i) \
;         __builtin_amdgcn_global_load_lds((const unsigned*)((const char*)(gbase) + (voff)[_i]), (LAS unsigned*)(lds + (bufoff) + ldsw + _i * 8192), 16, 0, 0); } while (0)
; #define PG8_WAIT_V(n) asm volatile("s_waitcnt vmcnt(" #n ")" ::: "memory")
; #define PG8_BAR __builtin_amdgcn_s_barrier()
; template <class Epi, class Sched, bool ALIGN_EPI>
; __device__ __forceinline__ void gemm_phase(LAS unsigned char* lds, const bf16_t* Ab, const bf16_t* Bb, int lda, int ldb, int K, const Sched& S, Epi& E) {
;     ...
;     f32x4 acc[2][2][4][2];
; #pragma unroll
;     for (int a = 0; a < 2; ++a)
; #pragma unroll
;         for (int b = 0; b < 2; ++b)
; #pragma unroll
;             for (int m = 0; m < 4; ++m)
; #pragma unroll
;                 for (int n = 0; n < 2; ++n) acc[a][b][m][n] = (f32x4){0.f, 0.f, 0.f, 0.f};
;     bf16x8 At[4][2], B0[2][2], B1[2][2];
;     const char* cA = (const char*)(Ab + cur.a_off); const char* cB = (const char*)(Bb + cur.b_off);
;     PG8_STAGE(PG8_SB(0, 0), cB, voffB); PG8_STAGE(PG8_SB(0, 1), cB + hstepB, voffB); PG8_STAGE(PG8_SA(0, 0), cA, voffA); PG8_STAGE(PG8_SA(0, 1), cA + hstepA, voffA);
;     if (wr == 1) PG8_BAR;
;     PG8_WAIT_V(2); PG8_BAR;
;     PG8_STAGE(PG8_SB(1, 0), cB + kstep, voffB); PG8_STAGE(PG8_SA(1, 0), cA + kstep, voffA); PG8_STAGE(PG8_SB(1, 1), cB + hstepB + kstep, voffB);
;     PG8_WAIT_V(6); PG8_BAR;
.LBB0_522:
	s_add_u32 s12, s52, 0xe800000
	s_addc_u32 s13, s53, 0
	s_lshl_b32 s6, s6, 5
	s_and_b32 s6, s6, 0x60
	s_add_i32 m0, s44, 0x18000
	v_lshl_add_u64 v[10:11], v[10:11], 0, s[26:27]
	s_lshl_b32 s67, s7, 6
	s_lshl_b32 s68, s7, 13
	s_lshl_b32 s69, s6, 7
	s_waitcnt vmcnt(2)
	s_barrier
	global_load_lds_dwordx4 v[10:11], off
	v_lshl_add_u64 v[8:9], v[8:9], 0, s[26:27]
	s_add_i32 m0, s44, 0x1a000
	s_add_i32 s70, s44, 0x8000
	s_add_i32 s71, s44, 0xa000
	global_load_lds_dwordx4 v[8:9], off
	v_lshl_add_u64 v[2:3], v[2:3], 0, s[26:27]
	s_mov_b32 m0, s70
	s_add_u32 s8, s60, 0x40080
	global_load_lds_dwordx4 v[2:3], off
	v_lshl_add_u64 v[2:3], v[6:7], 0, s[26:27]
	s_mov_b32 m0, s71
	s_addc_u32 s9, s61, 0
	global_load_lds_dwordx4 v[2:3], off
	s_add_i32 m0, s44, 0x1c000
	v_lshl_add_u64 v[2:3], s[8:9], 0, v[0:1]
	global_load_lds_dwordx4 v[2:3], off
	v_lshl_add_u64 v[2:3], s[8:9], 0, v[132:133]
	s_add_i32 m0, s44, 0x1e000
	v_and_b32_e32 v5, 48, v98
	global_load_lds_dwordx4 v[2:3], off
	v_lshlrev_b32_e32 v12, 6, v98
	s_cmpk_lt_u32 s25, 0x100
	v_and_or_b32 v5, v12, s89, v5
	v_lshlrev_b32_e32 v12, 2, v98
	s_waitcnt vmcnt(6)
	s_cselect_b64 s[14:15], -1, 0
	s_lshl_b32 s7, s7, 8
	v_and_b32_e32 v12, 32, v12
	s_add_i32 s72, s7, 0
	v_mov_b32_e32 v2, 0
	v_bitop3_b32 v140, v5, s68, v12 bitop3:0xde
	v_bitop3_b32 v141, s69, v5, v12 bitop3:0xf6
	s_add_i32 s72, s72, 0x22100
	s_mov_b32 s75, 0
	s_lshl_b32 s18, s6, 1
	v_mov_b32_e32 v134, v0
	v_mov_b32_e32 v0, v4
	v_mov_b32_e32 v3, v2
	v_mov_b32_e32 v4, v2
	v_mov_b32_e32 v5, v2
	v_mov_b32_e32 v6, v2
	v_mov_b32_e32 v7, v2
	v_mov_b32_e32 v8, v2
	v_mov_b32_e32 v9, v2
	v_mov_b32_e32 v10, v2
	v_mov_b32_e32 v11, v2
	v_mov_b32_e32 v12, v2
	v_mov_b32_e32 v13, v2
	v_mov_b32_e32 v14, v2
	v_mov_b32_e32 v15, v2
	v_mov_b32_e32 v16, v2
	v_mov_b32_e32 v17, v2
	v_mov_b32_e32 v18, v2
	v_mov_b32_e32 v19, v2
	v_mov_b32_e32 v20, v2
	v_mov_b32_e32 v21, v2
	v_mov_b32_e32 v22, v2
	v_mov_b32_e32 v23, v2
	v_mov_b32_e32 v24, v2
	v_mov_b32_e32 v25, v2
	v_mov_b32_e32 v26, v2
	v_mov_b32_e32 v27, v2
	v_mov_b32_e32 v28, v2
	v_mov_b32_e32 v29, v2
	v_mov_b32_e32 v30, v2
	v_mov_b32_e32 v31, v2
	v_mov_b32_e32 v32, v2
	v_mov_b32_e32 v33, v2
	v_mov_b32_e32 v34, v2
	v_mov_b32_e32 v35, v2
	v_mov_b32_e32 v36, v2
	v_mov_b32_e32 v37, v2
	v_mov_b32_e32 v38, v2
	v_mov_b32_e32 v39, v2
	v_mov_b32_e32 v40, v2
	v_mov_b32_e32 v41, v2
	v_mov_b32_e32 v42, v2
	v_mov_b32_e32 v43, v2
	v_mov_b32_e32 v44, v2
	v_mov_b32_e32 v45, v2
	v_mov_b32_e32 v46, v2
	v_mov_b32_e32 v47, v2
	v_mov_b32_e32 v48, v2
	v_mov_b32_e32 v49, v2
	v_mov_b32_e32 v50, v2
	v_mov_b32_e32 v51, v2
	v_mov_b32_e32 v52, v2
	v_mov_b32_e32 v53, v2
	v_mov_b32_e32 v54, v2
	v_mov_b32_e32 v55, v2
	v_mov_b32_e32 v56, v2
	v_mov_b32_e32 v57, v2
	v_mov_b32_e32 v58, v2
	v_mov_b32_e32 v59, v2
	v_mov_b32_e32 v60, v2
	v_mov_b32_e32 v61, v2
	v_mov_b32_e32 v62, v2
	v_mov_b32_e32 v63, v2
	v_mov_b32_e32 v64, v2
	v_mov_b32_e32 v65, v2
	v_mov_b32_e32 v66, v2
	v_mov_b32_e32 v67, v2
	v_mov_b32_e32 v68, v2
	v_mov_b32_e32 v69, v2
	v_mov_b32_e32 v70, v2
	v_mov_b32_e32 v71, v2
	v_mov_b32_e32 v72, v2
	v_mov_b32_e32 v73, v2
	v_mov_b32_e32 v74, v2
	v_mov_b32_e32 v75, v2
	v_mov_b32_e32 v76, v2
	v_mov_b32_e32 v77, v2
	v_mov_b32_e32 v78, v2
	v_mov_b32_e32 v79, v2
	v_mov_b32_e32 v80, v2
	v_mov_b32_e32 v81, v2
	v_mov_b32_e32 v82, v2
	v_mov_b32_e32 v83, v2
	v_mov_b32_e32 v84, v2
	v_mov_b32_e32 v85, v2
	v_mov_b32_e32 v86, v2
	v_mov_b32_e32 v87, v2
	v_mov_b32_e32 v88, v2
	v_mov_b32_e32 v89, v2
	v_mov_b32_e32 v90, v2
	v_mov_b32_e32 v91, v2
	v_mov_b32_e32 v92, v2
	v_mov_b32_e32 v93, v2
	v_mov_b32_e32 v94, v2
	v_mov_b32_e32 v95, v2
	v_mov_b32_e32 v96, v2
	v_mov_b32_e32 v97, v2
	v_mov_b32_e32 v98, v2
	v_mov_b32_e32 v99, v2
	v_mov_b32_e32 v100, v2
	v_mov_b32_e32 v101, v2
	v_mov_b32_e32 v102, v2
	v_mov_b32_e32 v103, v2
	v_mov_b32_e32 v104, v2
	v_mov_b32_e32 v105, v2
	v_mov_b32_e32 v106, v2
	v_mov_b32_e32 v107, v2
	v_mov_b32_e32 v108, v2
	v_mov_b32_e32 v109, v2
	v_mov_b32_e32 v110, v2
	v_mov_b32_e32 v111, v2
	v_mov_b32_e32 v112, v2
	v_mov_b32_e32 v113, v2
	v_mov_b32_e32 v114, v2
	v_mov_b32_e32 v115, v2
	v_mov_b32_e32 v116, v2
	v_mov_b32_e32 v117, v2
	v_mov_b32_e32 v118, v2
	v_mov_b32_e32 v119, v2
	v_mov_b32_e32 v120, v2
	v_mov_b32_e32 v121, v2
	v_mov_b32_e32 v122, v2
	v_mov_b32_e32 v123, v2
	v_mov_b32_e32 v124, v2
	v_mov_b32_e32 v125, v2
	v_mov_b32_e32 v126, v2
	v_mov_b32_e32 v127, v2
	v_mov_b32_e32 v128, v2
	v_mov_b32_e32 v129, v2
	s_barrier
	s_branch .LBB0_524

; #define PG8_STAGE(bufoff, gbase, voff) do { _Pragma("unroll") for (int _i = 0; _i < 2; ++_i) \
;         __builtin_amdgcn_global_load_lds((const unsigned*)((const char*)(gbase) + (voff)[_i]), (LAS unsigned*)(lds + (bufoff) + ldsw + _i * 8192), 16, 0, 0); } while (0)
; #define PG8_WAIT_V(n) asm volatile("s_waitcnt vmcnt(" #n ")" ::: "memory")
; #define PG8_BAR __builtin_amdgcn_s_barrier()
; template <class Epi, class Sched, bool ALIGN_EPI>
; __device__ __forceinline__ void gemm_phase(LAS unsigned char* lds, const bf16_t* Ab, const bf16_t* Bb, int lda, int ldb, int K, const Sched& S, Epi& E) {
;     ...
;     f32x4 acc[2][2][4][2];
; #pragma unroll
;     for (int a = 0; a < 2; ++a)
; #pragma unroll
;         for (int b = 0; b < 2; ++b)
; #pragma unroll
;             for (int m = 0; m < 4; ++m)
; #pragma unroll
;                 for (int n = 0; n < 2; ++n) acc[a][b][m][n] = (f32x4){0.f, 0.f, 0.f, 0.f};
;     bf16x8 At[4][2], B0[2][2], B1[2][2];
;     const char* cA = (const char*)(Ab + cur.a_off); const char* cB = (const char*)(Bb + cur.b_off);
;     PG8_STAGE(PG8_SB(0, 0), cB, voffB); PG8_STAGE(PG8_SB(0, 1), cB + hstepB, voffB); PG8_STAGE(PG8_SA(0, 0), cA, voffA); PG8_STAGE(PG8_SA(0, 1), cA + hstepA, voffA);
;     if (wr == 1) PG8_BAR;
;     PG8_WAIT_V(2); PG8_BAR;
;     PG8_STAGE(PG8_SB(1, 0), cB + kstep, voffB); PG8_STAGE(PG8_SA(1, 0), cA + kstep, voffA); PG8_STAGE(PG8_SB(1, 1), cB + hstepB + kstep, voffB);
;     PG8_WAIT_V(6); PG8_BAR;
.LBB0_740:
	s_add_u32 s54, s62, 0xe800000
	s_addc_u32 s55, s63, 0
	s_lshl_b32 s4, s4, 5
	s_and_b32 s4, s4, 0x60
	s_add_i32 m0, s47, 0x18000
	v_lshl_add_u64 v[10:11], v[10:11], 0, s[26:27]
	s_lshl_b32 s91, s6, 6
	s_lshl_b32 s92, s6, 13
	s_lshl_b32 s5, s4, 7
	s_waitcnt vmcnt(2)
	s_barrier
	global_load_lds_dwordx4 v[10:11], off
	v_lshl_add_u64 v[8:9], v[8:9], 0, s[26:27]
	s_add_i32 m0, s47, 0x1a000
	s_add_i32 s24, s47, 0x8000
	s_add_i32 s87, s47, 0xa000
	global_load_lds_dwordx4 v[8:9], off
	v_lshl_add_u64 v[2:3], v[2:3], 0, s[26:27]
	s_mov_b32 m0, s24
	s_add_u32 s8, s10, 0x40080
	global_load_lds_dwordx4 v[2:3], off
	v_lshl_add_u64 v[2:3], v[6:7], 0, s[26:27]
	s_mov_b32 m0, s87
	s_addc_u32 s9, s11, 0
	global_load_lds_dwordx4 v[2:3], off
	s_add_i32 m0, s47, 0x1c000
	v_lshl_add_u64 v[2:3], s[8:9], 0, v[0:1]
	global_load_lds_dwordx4 v[2:3], off
	v_lshl_add_u64 v[2:3], s[8:9], 0, v[132:133]
	s_add_i32 m0, s47, 0x1e000
	s_cmpk_lt_u32 s2, 0x100
	global_load_lds_dwordx4 v[2:3], off
	s_cselect_b64 s[56:57], -1, 0
	s_add_u32 s58, s62, 0x11000000
	s_addc_u32 s59, s63, 0
	s_add_u32 s60, s62, 0x13000000
	s_addc_u32 s61, s63, 0
	v_and_b32_e32 v5, 48, v98
	v_lshlrev_b32_e32 v12, 6, v98
	s_add_u32 s62, s62, 0x15000000
	v_and_or_b32 v5, v12, s89, v5
	v_lshlrev_b32_e32 v12, 2, v98
	s_waitcnt vmcnt(6)
	s_addc_u32 s63, s63, 0
	s_lshl_b32 s2, s6, 8
	v_and_b32_e32 v12, 32, v12
	s_add_i32 s2, s2, 0
	v_mov_b32_e32 v2, 0
	v_bitop3_b32 v160, v5, s92, v12 bitop3:0xde
	v_bitop3_b32 v161, s5, v5, v12 bitop3:0xf6
	s_add_i32 s2, s2, 0x22100
	s_mov_b32 s21, 0
	v_mov_b32_e32 v134, v0
	v_mov_b32_e32 v0, v4
	v_mov_b32_e32 v3, v2
	v_mov_b32_e32 v4, v2
	v_mov_b32_e32 v5, v2
	v_mov_b32_e32 v6, v2
	v_mov_b32_e32 v7, v2
	v_mov_b32_e32 v8, v2
	v_mov_b32_e32 v9, v2
	v_mov_b32_e32 v10, v2
	v_mov_b32_e32 v11, v2
	v_mov_b32_e32 v12, v2
	v_mov_b32_e32 v13, v2
	v_mov_b32_e32 v14, v2
	v_mov_b32_e32 v15, v2
	v_mov_b32_e32 v16, v2
	v_mov_b32_e32 v17, v2
	v_mov_b32_e32 v18, v2
	v_mov_b32_e32 v19, v2
	v_mov_b32_e32 v20, v2
	v_mov_b32_e32 v21, v2
	v_mov_b32_e32 v22, v2
	v_mov_b32_e32 v23, v2
	v_mov_b32_e32 v24, v2
	v_mov_b32_e32 v25, v2
	v_mov_b32_e32 v26, v2
	v_mov_b32_e32 v27, v2
	v_mov_b32_e32 v28, v2
	v_mov_b32_e32 v29, v2
	v_mov_b32_e32 v30, v2
	v_mov_b32_e32 v31, v2
	v_mov_b32_e32 v32, v2
	v_mov_b32_e32 v33, v2
	v_mov_b32_e32 v34, v2
	v_mov_b32_e32 v35, v2
	v_mov_b32_e32 v36, v2
	v_mov_b32_e32 v37, v2
	v_mov_b32_e32 v38, v2
	v_mov_b32_e32 v39, v2
	v_mov_b32_e32 v40, v2
	v_mov_b32_e32 v41, v2
	v_mov_b32_e32 v42, v2
	v_mov_b32_e32 v43, v2
	v_mov_b32_e32 v44, v2
	v_mov_b32_e32 v45, v2
	v_mov_b32_e32 v46, v2
	v_mov_b32_e32 v47, v2
	v_mov_b32_e32 v48, v2
	v_mov_b32_e32 v49, v2
	v_mov_b32_e32 v50, v2
	v_mov_b32_e32 v51, v2
	v_mov_b32_e32 v52, v2
	v_mov_b32_e32 v53, v2
	v_mov_b32_e32 v54, v2
	v_mov_b32_e32 v55, v2
	v_mov_b32_e32 v56, v2
	v_mov_b32_e32 v57, v2
	v_mov_b32_e32 v58, v2
	v_mov_b32_e32 v59, v2
	v_mov_b32_e32 v60, v2
	v_mov_b32_e32 v61, v2
	v_mov_b32_e32 v62, v2
	v_mov_b32_e32 v63, v2
	v_mov_b32_e32 v64, v2
	v_mov_b32_e32 v65, v2
	v_mov_b32_e32 v66, v2
	v_mov_b32_e32 v67, v2
	v_mov_b32_e32 v68, v2
	v_mov_b32_e32 v69, v2
	v_mov_b32_e32 v70, v2
	v_mov_b32_e32 v71, v2
	v_mov_b32_e32 v72, v2
	v_mov_b32_e32 v73, v2
	v_mov_b32_e32 v74, v2
	v_mov_b32_e32 v75, v2
	v_mov_b32_e32 v76, v2
	v_mov_b32_e32 v77, v2
	v_mov_b32_e32 v78, v2
	v_mov_b32_e32 v79, v2
	v_mov_b32_e32 v80, v2
	v_mov_b32_e32 v81, v2
	v_mov_b32_e32 v82, v2
	v_mov_b32_e32 v83, v2
	v_mov_b32_e32 v84, v2
	v_mov_b32_e32 v85, v2
	v_mov_b32_e32 v86, v2
	v_mov_b32_e32 v87, v2
	v_mov_b32_e32 v88, v2
	v_mov_b32_e32 v89, v2
	v_mov_b32_e32 v90, v2
	v_mov_b32_e32 v91, v2
	v_mov_b32_e32 v92, v2
	v_mov_b32_e32 v93, v2
	v_mov_b32_e32 v94, v2
	v_mov_b32_e32 v95, v2
	v_mov_b32_e32 v96, v2
	v_mov_b32_e32 v97, v2
	v_mov_b32_e32 v98, v2
	v_mov_b32_e32 v99, v2
	v_mov_b32_e32 v100, v2
	v_mov_b32_e32 v101, v2
	v_mov_b32_e32 v102, v2
	v_mov_b32_e32 v103, v2
	v_mov_b32_e32 v104, v2
	v_mov_b32_e32 v105, v2
	v_mov_b32_e32 v106, v2
	v_mov_b32_e32 v107, v2
	v_mov_b32_e32 v108, v2
	v_mov_b32_e32 v109, v2
	v_mov_b32_e32 v110, v2
	v_mov_b32_e32 v111, v2
	v_mov_b32_e32 v112, v2
	v_mov_b32_e32 v113, v2
	v_mov_b32_e32 v114, v2
	v_mov_b32_e32 v115, v2
	v_mov_b32_e32 v116, v2
	v_mov_b32_e32 v117, v2
	v_mov_b32_e32 v118, v2
	v_mov_b32_e32 v119, v2
	v_mov_b32_e32 v120, v2
	v_mov_b32_e32 v121, v2
	v_mov_b32_e32 v122, v2
	v_mov_b32_e32 v123, v2
	v_mov_b32_e32 v124, v2
	v_mov_b32_e32 v125, v2
	v_mov_b32_e32 v126, v2
	v_mov_b32_e32 v127, v2
	v_mov_b32_e32 v128, v2
	v_mov_b32_e32 v129, v2
	s_barrier
	s_branch .LBB0_742

; #define PG8_STAGE(bufoff, gbase, voff) do { _Pragma("unroll") for (int _i = 0; _i < 2; ++_i) \
;         __builtin_amdgcn_global_load_lds((const unsigned*)((const char*)(gbase) + (voff)[_i]), (LAS unsigned*)(lds + (bufoff) + ldsw + _i * 8192), 16, 0, 0); } while (0)
; #define PG8_WAIT_V(n) asm volatile("s_waitcnt vmcnt(" #n ")" ::: "memory")
; #define PG8_BAR __builtin_amdgcn_s_barrier()
; template <class Epi, class Sched, bool ALIGN_EPI>
; __device__ __forceinline__ void gemm_phase(LAS unsigned char* lds, const bf16_t* Ab, const bf16_t* Bb, int lda, int ldb, int K, const Sched& S, Epi& E) {
;     ...
;     f32x4 acc[2][2][4][2];
; #pragma unroll
;     for (int a = 0; a < 2; ++a)
; #pragma unroll
;         for (int b = 0; b < 2; ++b)
; #pragma unroll
;             for (int m = 0; m < 4; ++m)
; #pragma unroll
;                 for (int n = 0; n < 2; ++n) acc[a][b][m][n] = (f32x4){0.f, 0.f, 0.f, 0.f};
;     bf16x8 At[4][2], B0[2][2], B1[2][2];
;     const char* cA = (const char*)(Ab + cur.a_off); const char* cB = (const char*)(Bb + cur.b_off);
;     PG8_STAGE(PG8_SB(0, 0), cB, voffB); PG8_STAGE(PG8_SB(0, 1), cB + hstepB, voffB); PG8_STAGE(PG8_SA(0, 0), cA, voffA); PG8_STAGE(PG8_SA(0, 1), cA + hstepA, voffA);
;     if (wr == 1) PG8_BAR;
;     PG8_WAIT_V(2); PG8_BAR;
;     PG8_STAGE(PG8_SB(1, 0), cB + kstep, voffB); PG8_STAGE(PG8_SA(1, 0), cA + kstep, voffA); PG8_STAGE(PG8_SB(1, 1), cB + hstepB + kstep, voffB);
;     PG8_WAIT_V(6); PG8_BAR;
.LBB0_1492:
	v_readlane_b32 s8, v255, 13
	s_add_u32 s12, s52, 0xa800000
	v_readlane_b32 s9, v255, 14
	s_addc_u32 s13, s53, 0
	s_lshl_b64 s[8:9], s[8:9], 2
	s_add_u32 s8, s52, s8
	s_addc_u32 s9, s53, s9
	s_add_u32 s14, s8, 0x1d600000
	s_addc_u32 s15, s9, 0
	s_and_b32 s68, s7, 3
	s_add_i32 m0, s44, 0x18000
	v_lshl_add_u64 v[8:9], v[8:9], 0, s[26:27]
	s_lshl_b32 s69, s6, 6
	s_lshl_b32 s70, s6, 13
	s_lshl_b32 s71, s68, 5
	s_lshl_b32 s72, s68, 12
	s_waitcnt vmcnt(2)
	s_barrier
	global_load_lds_dwordx4 v[8:9], off
	v_lshl_add_u64 v[6:7], v[6:7], 0, s[26:27]
	s_add_i32 m0, s44, 0x1a000
	s_add_i32 s73, s44, 0x8000
	s_add_i32 s74, s44, 0xa000
	global_load_lds_dwordx4 v[6:7], off
	v_lshl_add_u64 v[2:3], v[2:3], 0, s[26:27]
	s_mov_b32 m0, s73
	s_add_u32 s8, s62, 0x40080
	global_load_lds_dwordx4 v[2:3], off
	v_lshl_add_u64 v[2:3], v[4:5], 0, s[26:27]
	s_mov_b32 m0, s74
	s_addc_u32 s9, s63, 0
	global_load_lds_dwordx4 v[2:3], off
	s_add_i32 m0, s44, 0x1c000
	v_lshl_add_u64 v[2:3], s[8:9], 0, v[0:1]
	global_load_lds_dwordx4 v[2:3], off
	v_lshl_add_u64 v[2:3], s[8:9], 0, v[158:159]
	s_add_i32 m0, s44, 0x1e000
	s_cmpk_lt_u32 s31, 0x100
	global_load_lds_dwordx4 v[2:3], off
	s_cselect_b64 s[16:17], -1, 0
	s_lshl_b32 s7, s68, 6
	v_and_b32_e32 v10, 48, v98
	v_lshlrev_b32_e32 v11, 6, v98
	s_add_u32 s75, s12, s7
	v_and_or_b32 v10, v11, s89, v10
	v_lshlrev_b32_e32 v11, 2, v98
	s_waitcnt vmcnt(6)
	s_addc_u32 s76, s13, 0
	s_lshl_b32 s6, s6, 8
	v_and_b32_e32 v11, 32, v11
	s_add_i32 s77, s6, 0
	v_mov_b32_e32 v2, 0
	v_bitop3_b32 v178, v10, s70, v11 bitop3:0xde
	v_bitop3_b32 v179, v10, s72, v11 bitop3:0xde
	s_add_i32 s77, s77, 0x22100
	s_mov_b32 s80, 0
	v_mov_b32_e32 v160, v0
	v_mov_b32_e32 v3, v2
	v_mov_b32_e32 v4, v2
	v_mov_b32_e32 v5, v2
	v_mov_b32_e32 v6, v2
	v_mov_b32_e32 v7, v2
	v_mov_b32_e32 v8, v2
	v_mov_b32_e32 v9, v2
	v_mov_b32_e32 v10, v2
	v_mov_b32_e32 v11, v2
	v_mov_b32_e32 v12, v2
	v_mov_b32_e32 v13, v2
	v_mov_b32_e32 v14, v2
	v_mov_b32_e32 v15, v2
	v_mov_b32_e32 v16, v2
	v_mov_b32_e32 v17, v2
	v_mov_b32_e32 v18, v2
	v_mov_b32_e32 v19, v2
	v_mov_b32_e32 v20, v2
	v_mov_b32_e32 v21, v2
	v_mov_b32_e32 v22, v2
	v_mov_b32_e32 v23, v2
	v_mov_b32_e32 v24, v2
	v_mov_b32_e32 v25, v2
	v_mov_b32_e32 v26, v2
	v_mov_b32_e32 v27, v2
	v_mov_b32_e32 v28, v2
	v_mov_b32_e32 v29, v2
	v_mov_b32_e32 v30, v2
	v_mov_b32_e32 v31, v2
	v_mov_b32_e32 v32, v2
	v_mov_b32_e32 v33, v2
	v_mov_b32_e32 v34, v2
	v_mov_b32_e32 v35, v2
	v_mov_b32_e32 v36, v2
	v_mov_b32_e32 v37, v2
	v_mov_b32_e32 v38, v2
	v_mov_b32_e32 v39, v2
	v_mov_b32_e32 v40, v2
	v_mov_b32_e32 v41, v2
	v_mov_b32_e32 v42, v2
	v_mov_b32_e32 v43, v2
	v_mov_b32_e32 v44, v2
	v_mov_b32_e32 v45, v2
	v_mov_b32_e32 v46, v2
	v_mov_b32_e32 v47, v2
	v_mov_b32_e32 v48, v2
	v_mov_b32_e32 v49, v2
	v_mov_b32_e32 v50, v2
	v_mov_b32_e32 v51, v2
	v_mov_b32_e32 v52, v2
	v_mov_b32_e32 v53, v2
	v_mov_b32_e32 v54, v2
	v_mov_b32_e32 v55, v2
	v_mov_b32_e32 v56, v2
	v_mov_b32_e32 v57, v2
	v_mov_b32_e32 v58, v2
	v_mov_b32_e32 v59, v2
	v_mov_b32_e32 v60, v2
	v_mov_b32_e32 v61, v2
	v_mov_b32_e32 v62, v2
	v_mov_b32_e32 v63, v2
	v_mov_b32_e32 v64, v2
	v_mov_b32_e32 v65, v2
	v_mov_b32_e32 v66, v2
	v_mov_b32_e32 v67, v2
	v_mov_b32_e32 v68, v2
	v_mov_b32_e32 v69, v2
	v_mov_b32_e32 v70, v2
	v_mov_b32_e32 v71, v2
	v_mov_b32_e32 v72, v2
	v_mov_b32_e32 v73, v2
	v_mov_b32_e32 v74, v2
	v_mov_b32_e32 v75, v2
	v_mov_b32_e32 v76, v2
	v_mov_b32_e32 v77, v2
	v_mov_b32_e32 v78, v2
	v_mov_b32_e32 v79, v2
	v_mov_b32_e32 v80, v2
	v_mov_b32_e32 v81, v2
	v_mov_b32_e32 v82, v2
	v_mov_b32_e32 v83, v2
	v_mov_b32_e32 v84, v2
	v_mov_b32_e32 v85, v2
	v_mov_b32_e32 v86, v2
	v_mov_b32_e32 v87, v2
	v_mov_b32_e32 v88, v2
	v_mov_b32_e32 v89, v2
	v_mov_b32_e32 v90, v2
	v_mov_b32_e32 v91, v2
	v_mov_b32_e32 v92, v2
	v_mov_b32_e32 v93, v2
	v_mov_b32_e32 v94, v2
	v_mov_b32_e32 v95, v2
	v_mov_b32_e32 v96, v2
	v_mov_b32_e32 v97, v2
	v_mov_b32_e32 v98, v2
	v_mov_b32_e32 v99, v2
	v_mov_b32_e32 v100, v2
	v_mov_b32_e32 v101, v2
	v_mov_b32_e32 v102, v2
	v_mov_b32_e32 v103, v2
	v_mov_b32_e32 v104, v2
	v_mov_b32_e32 v105, v2
	v_mov_b32_e32 v106, v2
	v_mov_b32_e32 v107, v2
	v_mov_b32_e32 v108, v2
	v_mov_b32_e32 v109, v2
	v_mov_b32_e32 v110, v2
	v_mov_b32_e32 v111, v2
	v_mov_b32_e32 v112, v2
	v_mov_b32_e32 v113, v2
	v_mov_b32_e32 v114, v2
	v_mov_b32_e32 v115, v2
	v_mov_b32_e32 v116, v2
	v_mov_b32_e32 v117, v2
	v_mov_b32_e32 v118, v2
	v_mov_b32_e32 v119, v2
	v_mov_b32_e32 v120, v2
	v_mov_b32_e32 v121, v2
	v_mov_b32_e32 v122, v2
	v_mov_b32_e32 v123, v2
	v_mov_b32_e32 v124, v2
	v_mov_b32_e32 v125, v2
	v_mov_b32_e32 v126, v2
	v_mov_b32_e32 v127, v2
	v_mov_b32_e32 v128, v2
	v_mov_b32_e32 v129, v2
	s_barrier
	s_branch .LBB0_1494

; #define PG8_STAGE(bufoff, gbase, voff) do { _Pragma("unroll") for (int _i = 0; _i < 2; ++_i) \
;         __builtin_amdgcn_global_load_lds((const unsigned*)((const char*)(gbase) + (voff)[_i]), (LAS unsigned*)(lds + (bufoff) + ldsw + _i * 8192), 16, 0, 0); } while (0)
; #define PG8_WAIT_V(n) asm volatile("s_waitcnt vmcnt(" #n ")" ::: "memory")
; #define PG8_BAR __builtin_amdgcn_s_barrier()
; template <class Epi, class Sched, bool ALIGN_EPI>
; __device__ __forceinline__ void gemm_phase(LAS unsigned char* lds, const bf16_t* Ab, const bf16_t* Bb, int lda, int ldb, int K, const Sched& S, Epi& E) {
;     ...
;     f32x4 acc[2][2][4][2];
; #pragma unroll
;     for (int a = 0; a < 2; ++a)
; #pragma unroll
;         for (int b = 0; b < 2; ++b)
; #pragma unroll
;             for (int m = 0; m < 4; ++m)
; #pragma unroll
;                 for (int n = 0; n < 2; ++n) acc[a][b][m][n] = (f32x4){0.f, 0.f, 0.f, 0.f};
;     bf16x8 At[4][2], B0[2][2], B1[2][2];
;     const char* cA = (const char*)(Ab + cur.a_off); const char* cB = (const char*)(Bb + cur.b_off);
;     PG8_STAGE(PG8_SB(0, 0), cB, voffB); PG8_STAGE(PG8_SB(0, 1), cB + hstepB, voffB); PG8_STAGE(PG8_SA(0, 0), cA, voffA); PG8_STAGE(PG8_SA(0, 1), cA + hstepA, voffA);
;     if (wr == 1) PG8_BAR;
;     PG8_WAIT_V(2); PG8_BAR;
;     PG8_STAGE(PG8_SB(1, 0), cB + kstep, voffB); PG8_STAGE(PG8_SA(1, 0), cA + kstep, voffA); PG8_STAGE(PG8_SB(1, 1), cB + hstepB + kstep, voffB);
;     PG8_WAIT_V(6); PG8_BAR;
.LBB0_1635:
	s_add_u32 s12, s52, 0xe800000
	s_addc_u32 s13, s53, 0
	s_lshl_b32 s6, s6, 5
	s_and_b32 s6, s6, 0x60
	s_add_i32 m0, s44, 0x18000
	v_lshl_add_u64 v[10:11], v[10:11], 0, s[26:27]
	s_lshl_b32 s47, s7, 6
	s_lshl_b32 s66, s7, 13
	s_lshl_b32 s67, s6, 7
	s_waitcnt vmcnt(2)
	s_barrier
	global_load_lds_dwordx4 v[10:11], off
	v_lshl_add_u64 v[8:9], v[8:9], 0, s[26:27]
	s_add_i32 m0, s44, 0x1a000
	s_add_i32 s68, s44, 0x8000
	s_add_i32 s69, s44, 0xa000
	global_load_lds_dwordx4 v[8:9], off
	v_lshl_add_u64 v[2:3], v[2:3], 0, s[26:27]
	s_mov_b32 m0, s68
	s_add_u32 s8, s60, 0x40080
	global_load_lds_dwordx4 v[2:3], off
	v_lshl_add_u64 v[2:3], v[6:7], 0, s[26:27]
	s_mov_b32 m0, s69
	s_addc_u32 s9, s61, 0
	global_load_lds_dwordx4 v[2:3], off
	s_add_i32 m0, s44, 0x1c000
	v_lshl_add_u64 v[2:3], s[8:9], 0, v[0:1]
	global_load_lds_dwordx4 v[2:3], off
	v_lshl_add_u64 v[2:3], s[8:9], 0, v[132:133]
	s_add_i32 m0, s44, 0x1e000
	v_and_b32_e32 v5, 48, v98
	global_load_lds_dwordx4 v[2:3], off
	v_lshlrev_b32_e32 v12, 6, v98
	s_cmpk_lt_u32 s62, 0x100
	v_and_or_b32 v5, v12, s89, v5
	v_lshlrev_b32_e32 v12, 2, v98
	s_waitcnt vmcnt(6)
	s_cselect_b64 s[14:15], -1, 0
	s_lshl_b32 s7, s7, 8
	v_and_b32_e32 v12, 32, v12
	s_add_i32 s70, s7, 0
	v_mov_b32_e32 v2, 0
	v_bitop3_b32 v140, v5, s66, v12 bitop3:0xde
	v_bitop3_b32 v141, s67, v5, v12 bitop3:0xf6
	s_add_i32 s70, s70, 0x22100
	s_mov_b32 s73, 0
	s_lshl_b32 s18, s6, 1
	v_mov_b32_e32 v134, v0
	v_mov_b32_e32 v0, v4
	v_mov_b32_e32 v3, v2
	v_mov_b32_e32 v4, v2
	v_mov_b32_e32 v5, v2
	v_mov_b32_e32 v6, v2
	v_mov_b32_e32 v7, v2
	v_mov_b32_e32 v8, v2
	v_mov_b32_e32 v9, v2
	v_mov_b32_e32 v10, v2
	v_mov_b32_e32 v11, v2
	v_mov_b32_e32 v12, v2
	v_mov_b32_e32 v13, v2
	v_mov_b32_e32 v14, v2
	v_mov_b32_e32 v15, v2
	v_mov_b32_e32 v16, v2
	v_mov_b32_e32 v17, v2
	v_mov_b32_e32 v18, v2
	v_mov_b32_e32 v19, v2
	v_mov_b32_e32 v20, v2
	v_mov_b32_e32 v21, v2
	v_mov_b32_e32 v22, v2
	v_mov_b32_e32 v23, v2
	v_mov_b32_e32 v24, v2
	v_mov_b32_e32 v25, v2
	v_mov_b32_e32 v26, v2
	v_mov_b32_e32 v27, v2
	v_mov_b32_e32 v28, v2
	v_mov_b32_e32 v29, v2
	v_mov_b32_e32 v30, v2
	v_mov_b32_e32 v31, v2
	v_mov_b32_e32 v32, v2
	v_mov_b32_e32 v33, v2
	v_mov_b32_e32 v34, v2
	v_mov_b32_e32 v35, v2
	v_mov_b32_e32 v36, v2
	v_mov_b32_e32 v37, v2
	v_mov_b32_e32 v38, v2
	v_mov_b32_e32 v39, v2
	v_mov_b32_e32 v40, v2
	v_mov_b32_e32 v41, v2
	v_mov_b32_e32 v42, v2
	v_mov_b32_e32 v43, v2
	v_mov_b32_e32 v44, v2
	v_mov_b32_e32 v45, v2
	v_mov_b32_e32 v46, v2
	v_mov_b32_e32 v47, v2
	v_mov_b32_e32 v48, v2
	v_mov_b32_e32 v49, v2
	v_mov_b32_e32 v50, v2
	v_mov_b32_e32 v51, v2
	v_mov_b32_e32 v52, v2
	v_mov_b32_e32 v53, v2
	v_mov_b32_e32 v54, v2
	v_mov_b32_e32 v55, v2
	v_mov_b32_e32 v56, v2
	v_mov_b32_e32 v57, v2
	v_mov_b32_e32 v58, v2
	v_mov_b32_e32 v59, v2
	v_mov_b32_e32 v60, v2
	v_mov_b32_e32 v61, v2
	v_mov_b32_e32 v62, v2
	v_mov_b32_e32 v63, v2
	v_mov_b32_e32 v64, v2
	v_mov_b32_e32 v65, v2
	v_mov_b32_e32 v66, v2
	v_mov_b32_e32 v67, v2
	v_mov_b32_e32 v68, v2
	v_mov_b32_e32 v69, v2
	v_mov_b32_e32 v70, v2
	v_mov_b32_e32 v71, v2
	v_mov_b32_e32 v72, v2
	v_mov_b32_e32 v73, v2
	v_mov_b32_e32 v74, v2
	v_mov_b32_e32 v75, v2
	v_mov_b32_e32 v76, v2
	v_mov_b32_e32 v77, v2
	v_mov_b32_e32 v78, v2
	v_mov_b32_e32 v79, v2
	v_mov_b32_e32 v80, v2
	v_mov_b32_e32 v81, v2
	v_mov_b32_e32 v82, v2
	v_mov_b32_e32 v83, v2
	v_mov_b32_e32 v84, v2
	v_mov_b32_e32 v85, v2
	v_mov_b32_e32 v86, v2
	v_mov_b32_e32 v87, v2
	v_mov_b32_e32 v88, v2
	v_mov_b32_e32 v89, v2
	v_mov_b32_e32 v90, v2
	v_mov_b32_e32 v91, v2
	v_mov_b32_e32 v92, v2
	v_mov_b32_e32 v93, v2
	v_mov_b32_e32 v94, v2
	v_mov_b32_e32 v95, v2
	v_mov_b32_e32 v96, v2
	v_mov_b32_e32 v97, v2
	v_mov_b32_e32 v98, v2
	v_mov_b32_e32 v99, v2
	v_mov_b32_e32 v100, v2
	v_mov_b32_e32 v101, v2
	v_mov_b32_e32 v102, v2
	v_mov_b32_e32 v103, v2
	v_mov_b32_e32 v104, v2
	v_mov_b32_e32 v105, v2
	v_mov_b32_e32 v106, v2
	v_mov_b32_e32 v107, v2
	v_mov_b32_e32 v108, v2
	v_mov_b32_e32 v109, v2
	v_mov_b32_e32 v110, v2
	v_mov_b32_e32 v111, v2
	v_mov_b32_e32 v112, v2
	v_mov_b32_e32 v113, v2
	v_mov_b32_e32 v114, v2
	v_mov_b32_e32 v115, v2
	v_mov_b32_e32 v116, v2
	v_mov_b32_e32 v117, v2
	v_mov_b32_e32 v118, v2
	v_mov_b32_e32 v119, v2
	v_mov_b32_e32 v120, v2
	v_mov_b32_e32 v121, v2
	v_mov_b32_e32 v122, v2
	v_mov_b32_e32 v123, v2
	v_mov_b32_e32 v124, v2
	v_mov_b32_e32 v125, v2
	v_mov_b32_e32 v126, v2
	v_mov_b32_e32 v127, v2
	v_mov_b32_e32 v128, v2
	v_mov_b32_e32 v129, v2
	s_barrier
	s_branch .LBB0_1637

; #define PG8_STAGE(bufoff, gbase, voff) do { _Pragma("unroll") for (int _i = 0; _i < 2; ++_i) \
;         __builtin_amdgcn_global_load_lds((const unsigned*)((const char*)(gbase) + (voff)[_i]), (LAS unsigned*)(lds + (bufoff) + ldsw + _i * 8192), 16, 0, 0); } while (0)
; #define PG8_WAIT_V(n) asm volatile("s_waitcnt vmcnt(" #n ")" ::: "memory")
; #define PG8_BAR __builtin_amdgcn_s_barrier()
; template <class Epi, class Sched, bool ALIGN_EPI>
; __device__ __forceinline__ void gemm_phase(LAS unsigned char* lds, const bf16_t* Ab, const bf16_t* Bb, int lda, int ldb, int K, const Sched& S, Epi& E) {
;     ...
;     f32x4 acc[2][2][4][2];
; #pragma unroll
;     for (int a = 0; a < 2; ++a)
; #pragma unroll
;         for (int b = 0; b < 2; ++b)
; #pragma unroll
;             for (int m = 0; m < 4; ++m)
; #pragma unroll
;                 for (int n = 0; n < 2; ++n) acc[a][b][m][n] = (f32x4){0.f, 0.f, 0.f, 0.f};
;     bf16x8 At[4][2], B0[2][2], B1[2][2];
;     const char* cA = (const char*)(Ab + cur.a_off); const char* cB = (const char*)(Bb + cur.b_off);
;     PG8_STAGE(PG8_SB(0, 0), cB, voffB); PG8_STAGE(PG8_SB(0, 1), cB + hstepB, voffB); PG8_STAGE(PG8_SA(0, 0), cA, voffA); PG8_STAGE(PG8_SA(0, 1), cA + hstepA, voffA);
;     if (wr == 1) PG8_BAR;
;     PG8_WAIT_V(2); PG8_BAR;
;     PG8_STAGE(PG8_SB(1, 0), cB + kstep, voffB); PG8_STAGE(PG8_SA(1, 0), cA + kstep, voffA); PG8_STAGE(PG8_SB(1, 1), cB + hstepB + kstep, voffB);
;     PG8_WAIT_V(6); PG8_BAR;
.LBB0_1997:
	s_add_u32 s12, s50, 0xe800000
	s_addc_u32 s13, s51, 0
	s_lshl_b32 s6, s6, 5
	s_and_b32 s6, s6, 0x60
	s_add_i32 m0, s44, 0x18000
	v_lshl_add_u64 v[10:11], v[10:11], 0, s[26:27]
	s_lshl_b32 s64, s7, 6
	s_lshl_b32 s65, s7, 13
	s_lshl_b32 s66, s6, 7
	s_waitcnt vmcnt(2)
	s_barrier
	global_load_lds_dwordx4 v[10:11], off
	v_lshl_add_u64 v[8:9], v[8:9], 0, s[26:27]
	s_add_i32 m0, s44, 0x1a000
	s_add_i32 s67, s44, 0x8000
	s_add_i32 s68, s44, 0xa000
	global_load_lds_dwordx4 v[8:9], off
	v_lshl_add_u64 v[2:3], v[2:3], 0, s[26:27]
	s_mov_b32 m0, s67
	s_add_u32 s8, s58, 0x40080
	global_load_lds_dwordx4 v[2:3], off
	v_lshl_add_u64 v[2:3], v[6:7], 0, s[26:27]
	s_mov_b32 m0, s68
	s_addc_u32 s9, s59, 0
	global_load_lds_dwordx4 v[2:3], off
	s_add_i32 m0, s44, 0x1c000
	v_lshl_add_u64 v[2:3], s[8:9], 0, v[0:1]
	global_load_lds_dwordx4 v[2:3], off
	v_lshl_add_u64 v[2:3], s[8:9], 0, v[132:133]
	s_add_i32 m0, s44, 0x1e000
	v_and_b32_e32 v5, 48, v98
	global_load_lds_dwordx4 v[2:3], off
	v_lshlrev_b32_e32 v12, 6, v98
	s_cmpk_lt_u32 s25, 0x100
	v_and_or_b32 v5, v12, s89, v5
	v_lshlrev_b32_e32 v12, 2, v98
	s_waitcnt vmcnt(6)
	s_cselect_b64 s[14:15], -1, 0
	s_lshl_b32 s7, s7, 8
	v_and_b32_e32 v12, 32, v12
	s_add_i32 s69, s7, 0
	v_mov_b32_e32 v2, 0
	v_bitop3_b32 v140, v5, s65, v12 bitop3:0xde
	v_bitop3_b32 v141, s66, v5, v12 bitop3:0xf6
	s_add_i32 s69, s69, 0x22100
	s_mov_b32 s72, 0
	s_lshl_b32 s18, s6, 1
	v_mov_b32_e32 v134, v0
	v_mov_b32_e32 v0, v4
	v_mov_b32_e32 v3, v2
	v_mov_b32_e32 v4, v2
	v_mov_b32_e32 v5, v2
	v_mov_b32_e32 v6, v2
	v_mov_b32_e32 v7, v2
	v_mov_b32_e32 v8, v2
	v_mov_b32_e32 v9, v2
	v_mov_b32_e32 v10, v2
	v_mov_b32_e32 v11, v2
	v_mov_b32_e32 v12, v2
	v_mov_b32_e32 v13, v2
	v_mov_b32_e32 v14, v2
	v_mov_b32_e32 v15, v2
	v_mov_b32_e32 v16, v2
	v_mov_b32_e32 v17, v2
	v_mov_b32_e32 v18, v2
	v_mov_b32_e32 v19, v2
	v_mov_b32_e32 v20, v2
	v_mov_b32_e32 v21, v2
	v_mov_b32_e32 v22, v2
	v_mov_b32_e32 v23, v2
	v_mov_b32_e32 v24, v2
	v_mov_b32_e32 v25, v2
	v_mov_b32_e32 v26, v2
	v_mov_b32_e32 v27, v2
	v_mov_b32_e32 v28, v2
	v_mov_b32_e32 v29, v2
	v_mov_b32_e32 v30, v2
	v_mov_b32_e32 v31, v2
	v_mov_b32_e32 v32, v2
	v_mov_b32_e32 v33, v2
	v_mov_b32_e32 v34, v2
	v_mov_b32_e32 v35, v2
	v_mov_b32_e32 v36, v2
	v_mov_b32_e32 v37, v2
	v_mov_b32_e32 v38, v2
	v_mov_b32_e32 v39, v2
	v_mov_b32_e32 v40, v2
	v_mov_b32_e32 v41, v2
	v_mov_b32_e32 v42, v2
	v_mov_b32_e32 v43, v2
	v_mov_b32_e32 v44, v2
	v_mov_b32_e32 v45, v2
	v_mov_b32_e32 v46, v2
	v_mov_b32_e32 v47, v2
	v_mov_b32_e32 v48, v2
	v_mov_b32_e32 v49, v2
	v_mov_b32_e32 v50, v2
	v_mov_b32_e32 v51, v2
	v_mov_b32_e32 v52, v2
	v_mov_b32_e32 v53, v2
	v_mov_b32_e32 v54, v2
	v_mov_b32_e32 v55, v2
	v_mov_b32_e32 v56, v2
	v_mov_b32_e32 v57, v2
	v_mov_b32_e32 v58, v2
	v_mov_b32_e32 v59, v2
	v_mov_b32_e32 v60, v2
	v_mov_b32_e32 v61, v2
	v_mov_b32_e32 v62, v2
	v_mov_b32_e32 v63, v2
	v_mov_b32_e32 v64, v2
	v_mov_b32_e32 v65, v2
	v_mov_b32_e32 v66, v2
	v_mov_b32_e32 v67, v2
	v_mov_b32_e32 v68, v2
	v_mov_b32_e32 v69, v2
	v_mov_b32_e32 v70, v2
	v_mov_b32_e32 v71, v2
	v_mov_b32_e32 v72, v2
	v_mov_b32_e32 v73, v2
	v_mov_b32_e32 v74, v2
	v_mov_b32_e32 v75, v2
	v_mov_b32_e32 v76, v2
	v_mov_b32_e32 v77, v2
	v_mov_b32_e32 v78, v2
	v_mov_b32_e32 v79, v2
	v_mov_b32_e32 v80, v2
	v_mov_b32_e32 v81, v2
	v_mov_b32_e32 v82, v2
	v_mov_b32_e32 v83, v2
	v_mov_b32_e32 v84, v2
	v_mov_b32_e32 v85, v2
	v_mov_b32_e32 v86, v2
	v_mov_b32_e32 v87, v2
	v_mov_b32_e32 v88, v2
	v_mov_b32_e32 v89, v2
	v_mov_b32_e32 v90, v2
	v_mov_b32_e32 v91, v2
	v_mov_b32_e32 v92, v2
	v_mov_b32_e32 v93, v2
	v_mov_b32_e32 v94, v2
	v_mov_b32_e32 v95, v2
	v_mov_b32_e32 v96, v2
	v_mov_b32_e32 v97, v2
	v_mov_b32_e32 v98, v2
	v_mov_b32_e32 v99, v2
	v_mov_b32_e32 v100, v2
	v_mov_b32_e32 v101, v2
	v_mov_b32_e32 v102, v2
	v_mov_b32_e32 v103, v2
	v_mov_b32_e32 v104, v2
	v_mov_b32_e32 v105, v2
	v_mov_b32_e32 v106, v2
	v_mov_b32_e32 v107, v2
	v_mov_b32_e32 v108, v2
	v_mov_b32_e32 v109, v2
	v_mov_b32_e32 v110, v2
	v_mov_b32_e32 v111, v2
	v_mov_b32_e32 v112, v2
	v_mov_b32_e32 v113, v2
	v_mov_b32_e32 v114, v2
	v_mov_b32_e32 v115, v2
	v_mov_b32_e32 v116, v2
	v_mov_b32_e32 v117, v2
	v_mov_b32_e32 v118, v2
	v_mov_b32_e32 v119, v2
	v_mov_b32_e32 v120, v2
	v_mov_b32_e32 v121, v2
	v_mov_b32_e32 v122, v2
	v_mov_b32_e32 v123, v2
	v_mov_b32_e32 v124, v2
	v_mov_b32_e32 v125, v2
	v_mov_b32_e32 v126, v2
	v_mov_b32_e32 v127, v2
	v_mov_b32_e32 v128, v2
	v_mov_b32_e32 v129, v2
	s_barrier
	s_branch .LBB0_1999
